# token-0 f32 shadow MLP-down GEMM (K=4096): f32 matrix cores v_mfma_f32_16x16x4_f32 instead of VALU pk_fma + 32 cross-lane LDS hops; weight loads of a chunk issued together; LDS fill loads issued 32 at
# speedup vs baseline: 1.0140x; 1.0140x over previous
; template <int M> DEVI float shx(float v) { return __int_as_float(__builtin_amdgcn_ds_swizzle(__float_as_int(v), (M << 10) | 0x1f)); }
; DEVI void sk_gemm(const float* __restrict__ A, int lda, int K, const float* __restrict__ W, int N, const float* __restrict__ gain,
;                   bool use_rs, float* __restrict__ out, int ldo, int mode, unsigned char* lds, int wv, int bid, int nblk) {
;     ...
;       __syncthreads();
;       {
;         const int b = tid >> 5, j = tid & 31; float ss = 0.f;
; #pragma unroll 8
;         for (int k = j; k < kc; k += 32) { const float v = A[(size_t)b * lda + k0 + k]; ss += v * v; As[b * 1024 + k] = v * gain[k0 + k]; }
;         if (use_rs) { ss += shx<16>(ss); ss += shx<8>(ss); ss += shx<4>(ss); ss += shx<2>(ss); ss += shx<1>(ss); if (j == 0) rsS[b] = rsqrtf(ss / (float)K + 1e-6f); }
;       }
;       __syncthreads();
.LBB0_373:
	v_mov_b32_e32 v32, v2
	v_lshl_add_u64 v[182:183], v[32:33], 2, v[0:1]
	v_add_u32_e32 v32, s8, v2
	v_lshl_add_u64 v[184:185], v[32:33], 2, s[90:91]
	global_load_dword v186, v[182:183], off offset:0
	global_load_dword v187, v[182:183], off offset:128
	global_load_dword v188, v[182:183], off offset:256
	global_load_dword v189, v[182:183], off offset:384
	global_load_dword v190, v[182:183], off offset:512
	global_load_dword v191, v[182:183], off offset:640
	global_load_dword v192, v[182:183], off offset:768
	global_load_dword v193, v[182:183], off offset:896
	global_load_dword v194, v[182:183], off offset:1024
	global_load_dword v195, v[182:183], off offset:1152
	global_load_dword v196, v[182:183], off offset:1280
	global_load_dword v197, v[182:183], off offset:1408
	global_load_dword v198, v[182:183], off offset:1536
	global_load_dword v199, v[182:183], off offset:1664
	global_load_dword v200, v[182:183], off offset:1792
	global_load_dword v201, v[182:183], off offset:1920
	global_load_dword v202, v[184:185], off offset:0
	global_load_dword v203, v[184:185], off offset:128
	global_load_dword v204, v[184:185], off offset:256
	global_load_dword v205, v[184:185], off offset:384
	global_load_dword v206, v[184:185], off offset:512
	global_load_dword v207, v[184:185], off offset:640
	global_load_dword v208, v[184:185], off offset:768
	global_load_dword v209, v[184:185], off offset:896
	global_load_dword v210, v[184:185], off offset:1024
	global_load_dword v211, v[184:185], off offset:1152
	global_load_dword v212, v[184:185], off offset:1280
	global_load_dword v213, v[184:185], off offset:1408
	global_load_dword v214, v[184:185], off offset:1536
	global_load_dword v215, v[184:185], off offset:1664
	global_load_dword v216, v[184:185], off offset:1792
	global_load_dword v217, v[184:185], off offset:1920
	v_add_u32_e32 v218, 0x0, v44
	s_waitcnt vmcnt(14)
	v_mul_f32_e32 v186, v186, v202
	v_mul_f32_e32 v187, v187, v203
	ds_write2_b32 v218, v186, v187 offset1:32
	s_waitcnt vmcnt(12)
	v_mul_f32_e32 v188, v188, v204
	v_mul_f32_e32 v189, v189, v205
	ds_write2_b32 v218, v188, v189 offset0:64 offset1:96
	s_waitcnt vmcnt(10)
	v_mul_f32_e32 v190, v190, v206
	v_mul_f32_e32 v191, v191, v207
	ds_write2_b32 v218, v190, v191 offset0:128 offset1:160
	s_waitcnt vmcnt(8)
	v_mul_f32_e32 v192, v192, v208
	v_mul_f32_e32 v193, v193, v209
	ds_write2_b32 v218, v192, v193 offset0:192 offset1:224
	v_add_u32_e32 v218, 0x400, v44
	s_waitcnt vmcnt(6)
	v_mul_f32_e32 v194, v194, v210
	v_mul_f32_e32 v195, v195, v211
	ds_write2_b32 v218, v194, v195 offset1:32
	s_waitcnt vmcnt(4)
	v_mul_f32_e32 v196, v196, v212
	v_mul_f32_e32 v197, v197, v213
	ds_write2_b32 v218, v196, v197 offset0:64 offset1:96
	s_waitcnt vmcnt(2)
	v_mul_f32_e32 v198, v198, v214
	v_mul_f32_e32 v199, v199, v215
	ds_write2_b32 v218, v198, v199 offset0:128 offset1:160
	s_waitcnt vmcnt(0)
	v_mul_f32_e32 v200, v200, v216
	v_mul_f32_e32 v201, v201, v217
	ds_write2_b32 v218, v200, v201 offset0:192 offset1:224
	global_load_dword v186, v[182:183], off offset:2048
	global_load_dword v187, v[182:183], off offset:2176
	global_load_dword v188, v[182:183], off offset:2304
	global_load_dword v189, v[182:183], off offset:2432
	global_load_dword v190, v[182:183], off offset:2560
	global_load_dword v191, v[182:183], off offset:2688
	global_load_dword v192, v[182:183], off offset:2816
	global_load_dword v193, v[182:183], off offset:2944
	global_load_dword v194, v[182:183], off offset:3072
	global_load_dword v195, v[182:183], off offset:3200
	global_load_dword v196, v[182:183], off offset:3328
	global_load_dword v197, v[182:183], off offset:3456
	global_load_dword v198, v[182:183], off offset:3584
	global_load_dword v199, v[182:183], off offset:3712
	global_load_dword v200, v[182:183], off offset:3840
	global_load_dword v201, v[182:183], off offset:3968
	global_load_dword v202, v[184:185], off offset:2048
	global_load_dword v203, v[184:185], off offset:2176
	global_load_dword v204, v[184:185], off offset:2304
	global_load_dword v205, v[184:185], off offset:2432
	global_load_dword v206, v[184:185], off offset:2560
	global_load_dword v207, v[184:185], off offset:2688
	global_load_dword v208, v[184:185], off offset:2816
	global_load_dword v209, v[184:185], off offset:2944
	global_load_dword v210, v[184:185], off offset:3072
	global_load_dword v211, v[184:185], off offset:3200
	global_load_dword v212, v[184:185], off offset:3328
	global_load_dword v213, v[184:185], off offset:3456
	global_load_dword v214, v[184:185], off offset:3584
	global_load_dword v215, v[184:185], off offset:3712
	global_load_dword v216, v[184:185], off offset:3840
	global_load_dword v217, v[184:185], off offset:3968
	v_add_u32_e32 v218, 0x800, v44
	s_waitcnt vmcnt(14)
	v_mul_f32_e32 v186, v186, v202
	v_mul_f32_e32 v187, v187, v203
	ds_write2_b32 v218, v186, v187 offset1:32
	s_waitcnt vmcnt(12)
	v_mul_f32_e32 v188, v188, v204
	v_mul_f32_e32 v189, v189, v205
	ds_write2_b32 v218, v188, v189 offset0:64 offset1:96
	s_waitcnt vmcnt(10)
	v_mul_f32_e32 v190, v190, v206
	v_mul_f32_e32 v191, v191, v207
	ds_write2_b32 v218, v190, v191 offset0:128 offset1:160
	s_waitcnt vmcnt(8)
	v_mul_f32_e32 v192, v192, v208
	v_mul_f32_e32 v193, v193, v209
	ds_write2_b32 v218, v192, v193 offset0:192 offset1:224
	v_add_u32_e32 v218, 0xc00, v44
	s_waitcnt vmcnt(6)
	v_mul_f32_e32 v194, v194, v210
	v_mul_f32_e32 v195, v195, v211
	ds_write2_b32 v218, v194, v195 offset1:32
	s_waitcnt vmcnt(4)
	v_mul_f32_e32 v196, v196, v212
	v_mul_f32_e32 v197, v197, v213
	ds_write2_b32 v218, v196, v197 offset0:64 offset1:96
	s_waitcnt vmcnt(2)
	v_mul_f32_e32 v198, v198, v214
	v_mul_f32_e32 v199, v199, v215
	ds_write2_b32 v218, v198, v199 offset0:128 offset1:160
	s_waitcnt vmcnt(0)
	v_mul_f32_e32 v200, v200, v216
	v_mul_f32_e32 v201, v201, v217
	ds_write2_b32 v218, v200, v201 offset0:192 offset1:224
	v_ashrrev_i32_e32 v15, 31, v14
	v_lshlrev_b64 v[0:1], 12, v[14:15]
	v_lshl_add_u64 v[34:35], v[12:13], 0, v[0:1]
	s_mov_b32 s3, -4
	v_mov_b32_e32 v11, v46
	s_mov_b64 s[10:11], 0x8000
	s_waitcnt lgkmcnt(0)
	s_barrier
; template <int M> DEVI float shx(float v) { return __int_as_float(__builtin_amdgcn_ds_swizzle(__float_as_int(v), (M << 10) | 0x1f)); }
; DEVI float shx32(float v, int lane) { return __int_as_float(__builtin_amdgcn_ds_bpermute((lane ^ 32) << 2, __float_as_int(v))); }
; DEVI void sk_gemm(const float* __restrict__ A, int lda, int K, const float* __restrict__ W, int N, const float* __restrict__ gain,
;                   bool use_rs, float* __restrict__ out, int ldo, int mode, unsigned char* lds, int wv, int bid, int nblk) {
;     ...
;       const int ks = kc >> 5;
;       const int kb = (wave * 4 + kq) * ks;
;       const float* Wp = W + (size_t)(k0 + kb) * N + nl;
;       const float* Ap = As + kb;
; #pragma unroll 2
;       for (int k = 0; k < ks; k += 4) {
;         const float w0 = Wp[(size_t)(k + 0) * N], w1 = Wp[(size_t)(k + 1) * N], w2 = Wp[(size_t)(k + 2) * N], w3 = Wp[(size_t)(k + 3) * N];
; #pragma unroll
;         for (int b = 0; b < 16; ++b) { const float4 a = *(const float4*)(Ap + b * 1024 + k); acc[b] += a.x * w0 + a.y * w1 + a.z * w2 + a.w * w3; }
;       }
;     }
; #pragma unroll
;     for (int b = 0; b < 16; ++b) { float v = acc[b]; v += shx<16>(v); v += shx32(v, lane); if (kq == 0) red[(wave * 16 + b) * 16 + c16] = v; }
;     __syncthreads();
;     if (tid < 256) {
;       const int b = tid >> 4, c = tid & 15; float v = 0.f;
; #pragma unroll
;       for (int w = 0; w < 8; ++w) v += red[(w * 16 + b) * 16 + c];
;       const int nn = grp * 16 + c;
;       if (nn < N) {
;         if (use_rs) v *= rsS[b];
;         float* o = out + (size_t)b * ldo + nn;
;         if (mode == 1) *o += v; else if (mode == 2) { v = fmaxf(v, 0.f); *o = v * v; } else *o = v;
;       }
.LBB0_375:
	s_mov_b64 s[10:11], 0x2000
	v_add_co_u32_e64 v20, s[4:5], s85, v34
	s_nop 0
	v_addc_co_u32_e64 v21, s[4:5], -1, v35, s[4:5]
	global_load_dword v186, v[20:21], off offset:-4096
	global_load_dword v187, v[20:21], off
	v_lshl_add_u64 v[20:21], v[20:21], 0, s[10:11]
	global_load_dword v188, v[20:21], off offset:-4096
	global_load_dword v189, v[20:21], off
	v_lshl_add_u64 v[20:21], v[20:21], 0, s[10:11]
	global_load_dword v190, v[20:21], off offset:-4096
	global_load_dword v191, v[20:21], off
	v_lshl_add_u64 v[20:21], v[20:21], 0, s[10:11]
	global_load_dword v192, v[20:21], off offset:-4096
	global_load_dword v193, v[20:21], off
	v_lshl_add_u64 v[20:21], v[20:21], 0, s[10:11]
	global_load_dword v194, v[20:21], off offset:-4096
	global_load_dword v195, v[20:21], off
	v_lshl_add_u64 v[20:21], v[20:21], 0, s[10:11]
	global_load_dword v196, v[20:21], off offset:-4096
	global_load_dword v197, v[20:21], off
	v_lshl_add_u64 v[20:21], v[20:21], 0, s[10:11]
	global_load_dword v198, v[20:21], off offset:-4096
	global_load_dword v199, v[20:21], off
	v_lshl_add_u64 v[20:21], v[20:21], 0, s[10:11]
	global_load_dword v200, v[20:21], off offset:-4096
	global_load_dword v201, v[20:21], off
	v_lshl_add_u64 v[20:21], v[20:21], 0, s[10:11]
	global_load_dword v202, v[20:21], off offset:-4096
	global_load_dword v203, v[20:21], off
	v_lshl_add_u64 v[20:21], v[20:21], 0, s[10:11]
	global_load_dword v204, v[20:21], off offset:-4096
	global_load_dword v205, v[20:21], off
	v_lshl_add_u64 v[20:21], v[20:21], 0, s[10:11]
	global_load_dword v206, v[20:21], off offset:-4096
	global_load_dword v207, v[20:21], off
	v_lshl_add_u64 v[20:21], v[20:21], 0, s[10:11]
	global_load_dword v208, v[20:21], off offset:-4096
	global_load_dword v209, v[20:21], off
	v_lshl_add_u64 v[20:21], v[20:21], 0, s[10:11]
	global_load_dword v210, v[20:21], off offset:-4096
	global_load_dword v211, v[20:21], off
	v_lshl_add_u64 v[20:21], v[20:21], 0, s[10:11]
	global_load_dword v212, v[20:21], off offset:-4096
	global_load_dword v213, v[20:21], off
	v_lshl_add_u64 v[20:21], v[20:21], 0, s[10:11]
	global_load_dword v214, v[20:21], off offset:-4096
	global_load_dword v215, v[20:21], off
	v_lshl_add_u64 v[20:21], v[20:21], 0, s[10:11]
	global_load_dword v216, v[20:21], off offset:-4096
	global_load_dword v217, v[20:21], off
	v_mbcnt_lo_u32_b32 v22, -1, 0
	v_mbcnt_hi_u32_b32 v22, -1, v22
	v_and_b32_e32 v22, 15, v22
	v_lshl_add_u32 v23, v22, 12, v46
	ds_read_b128 v[182:185], v23
	ds_read_b128 v[218:221], v23 offset:16
	s_waitcnt vmcnt(28) lgkmcnt(1)
	v_mfma_f32_16x16x4_f32 v[16:19], v182, v186, v[16:19]
	v_mfma_f32_16x16x4_f32 v[16:19], v183, v187, v[16:19]
	v_mfma_f32_16x16x4_f32 v[16:19], v184, v188, v[16:19]
	v_mfma_f32_16x16x4_f32 v[16:19], v185, v189, v[16:19]
	ds_read_b128 v[182:185], v23 offset:32
	s_waitcnt vmcnt(24) lgkmcnt(1)
	v_mfma_f32_16x16x4_f32 v[16:19], v218, v190, v[16:19]
	v_mfma_f32_16x16x4_f32 v[16:19], v219, v191, v[16:19]
	v_mfma_f32_16x16x4_f32 v[16:19], v220, v192, v[16:19]
	v_mfma_f32_16x16x4_f32 v[16:19], v221, v193, v[16:19]
	ds_read_b128 v[218:221], v23 offset:48
	s_waitcnt vmcnt(20) lgkmcnt(1)
	v_mfma_f32_16x16x4_f32 v[16:19], v182, v194, v[16:19]
	v_mfma_f32_16x16x4_f32 v[16:19], v183, v195, v[16:19]
	v_mfma_f32_16x16x4_f32 v[16:19], v184, v196, v[16:19]
	v_mfma_f32_16x16x4_f32 v[16:19], v185, v197, v[16:19]
	ds_read_b128 v[182:185], v23 offset:64
	s_waitcnt vmcnt(16) lgkmcnt(1)
	v_mfma_f32_16x16x4_f32 v[16:19], v218, v198, v[16:19]
	v_mfma_f32_16x16x4_f32 v[16:19], v219, v199, v[16:19]
	v_mfma_f32_16x16x4_f32 v[16:19], v220, v200, v[16:19]
	v_mfma_f32_16x16x4_f32 v[16:19], v221, v201, v[16:19]
	ds_read_b128 v[218:221], v23 offset:80
	s_waitcnt vmcnt(12) lgkmcnt(1)
	v_mfma_f32_16x16x4_f32 v[16:19], v182, v202, v[16:19]
	v_mfma_f32_16x16x4_f32 v[16:19], v183, v203, v[16:19]
	v_mfma_f32_16x16x4_f32 v[16:19], v184, v204, v[16:19]
	v_mfma_f32_16x16x4_f32 v[16:19], v185, v205, v[16:19]
	ds_read_b128 v[182:185], v23 offset:96
	s_waitcnt vmcnt(8) lgkmcnt(1)
	v_mfma_f32_16x16x4_f32 v[16:19], v218, v206, v[16:19]
	v_mfma_f32_16x16x4_f32 v[16:19], v219, v207, v[16:19]
	v_mfma_f32_16x16x4_f32 v[16:19], v220, v208, v[16:19]
	v_mfma_f32_16x16x4_f32 v[16:19], v221, v209, v[16:19]
	ds_read_b128 v[218:221], v23 offset:112
	s_waitcnt vmcnt(4) lgkmcnt(1)
	v_mfma_f32_16x16x4_f32 v[16:19], v182, v210, v[16:19]
	v_mfma_f32_16x16x4_f32 v[16:19], v183, v211, v[16:19]
	v_mfma_f32_16x16x4_f32 v[16:19], v184, v212, v[16:19]
	v_mfma_f32_16x16x4_f32 v[16:19], v185, v213, v[16:19]
	s_waitcnt vmcnt(0) lgkmcnt(0)
	v_mfma_f32_16x16x4_f32 v[16:19], v218, v214, v[16:19]
	v_mfma_f32_16x16x4_f32 v[16:19], v219, v215, v[16:19]
	v_mfma_f32_16x16x4_f32 v[16:19], v220, v216, v[16:19]
	v_mfma_f32_16x16x4_f32 v[16:19], v221, v217, v[16:19]
	s_add_i32 s3, s8, 0x400
	v_add_u32_e32 v14, 0x400, v14
	s_cmpk_gt_u32 s8, 0xbff
	s_mov_b32 s8, s3
	s_cbranch_scc0 .LBB0_372
	s_nop 7
	s_nop 3
	v_mbcnt_lo_u32_b32 v22, -1, 0
	v_mbcnt_hi_u32_b32 v22, -1, v22
	v_lshrrev_b32_e32 v22, 4, v22
	v_lshl_add_u32 v22, v22, 8, v47
	ds_write_b32 v22, v16
	ds_write_b32 v22, v17 offset:64
	ds_write_b32 v22, v18 offset:128
	ds_write_b32 v22, v19 offset:192
	v_lshl_or_b32 v0, s2, 4, v41
	s_movk_i32 s3, 0x400
	v_cmp_gt_i32_e64 s[4:5], s3, v0
	s_and_b64 s[8:9], s[0:1], s[4:5]
	s_waitcnt lgkmcnt(0)
	s_barrier
	s_and_saveexec_b64 s[4:5], s[8:9]
	s_cbranch_execz .LBB0_370
	ds_read2st64_b32 v[2:3], v43 offset1:4
	v_ashrrev_i32_e32 v1, 31, v0
	v_lshl_add_u64 v[0:1], v[0:1], 2, v[8:9]
	s_waitcnt lgkmcnt(0)
	v_add_f32_e32 v2, 0, v2
	v_add_f32_e32 v11, v2, v3
	ds_read2st64_b32 v[2:3], v43 offset0:8 offset1:12
	s_waitcnt lgkmcnt(0)
	v_add_f32_e32 v2, v11, v2
	v_add_f32_e32 v11, v2, v3
	ds_read2st64_b32 v[2:3], v43 offset0:16 offset1:20
	s_waitcnt lgkmcnt(0)
	v_add_f32_e32 v2, v11, v2
	v_add_f32_e32 v11, v2, v3
	ds_read2st64_b32 v[2:3], v43 offset0:24 offset1:28
	s_waitcnt lgkmcnt(0)
	v_add_f32_e32 v2, v11, v2
	v_add_f32_e32 v2, v2, v3
	global_load_dword v3, v[0:1], off
	s_waitcnt vmcnt(0)
	v_add_f32_e32 v2, v2, v3
	global_store_dword v[0:1], v2, off
	s_branch .LBB0_370

; template <int M> DEVI float shx(float v) { return __int_as_float(__builtin_amdgcn_ds_swizzle(__float_as_int(v), (M << 10) | 0x1f)); }
; DEVI void sk_gemm(const float* __restrict__ A, int lda, int K, const float* __restrict__ W, int N, const float* __restrict__ gain,
;                   bool use_rs, float* __restrict__ out, int ldo, int mode, unsigned char* lds, int wv, int bid, int nblk) {
;     ...
;       __syncthreads();
;       {
;         const int b = tid >> 5, j = tid & 31; float ss = 0.f;
; #pragma unroll 8
;         for (int k = j; k < kc; k += 32) { const float v = A[(size_t)b * lda + k0 + k]; ss += v * v; As[b * 1024 + k] = v * gain[k0 + k]; }
;         if (use_rs) { ss += shx<16>(ss); ss += shx<8>(ss); ss += shx<4>(ss); ss += shx<2>(ss); ss += shx<1>(ss); if (j == 0) rsS[b] = rsqrtf(ss / (float)K + 1e-6f); }
;       }
;       __syncthreads();
.LBB0_1009:
	v_mov_b32_e32 v32, v2
	v_lshl_add_u64 v[182:183], v[32:33], 2, v[0:1]
	v_add_u32_e32 v32, s16, v2
	v_lshl_add_u64 v[184:185], v[32:33], 2, s[90:91]
	global_load_dword v186, v[182:183], off offset:0
	global_load_dword v187, v[182:183], off offset:128
	global_load_dword v188, v[182:183], off offset:256
	global_load_dword v189, v[182:183], off offset:384
	global_load_dword v190, v[182:183], off offset:512
	global_load_dword v191, v[182:183], off offset:640
	global_load_dword v192, v[182:183], off offset:768
	global_load_dword v193, v[182:183], off offset:896
	global_load_dword v194, v[182:183], off offset:1024
	global_load_dword v195, v[182:183], off offset:1152
	global_load_dword v196, v[182:183], off offset:1280
	global_load_dword v197, v[182:183], off offset:1408
	global_load_dword v198, v[182:183], off offset:1536
	global_load_dword v199, v[182:183], off offset:1664
	global_load_dword v200, v[182:183], off offset:1792
	global_load_dword v201, v[182:183], off offset:1920
	global_load_dword v202, v[184:185], off offset:0
	global_load_dword v203, v[184:185], off offset:128
	global_load_dword v204, v[184:185], off offset:256
	global_load_dword v205, v[184:185], off offset:384
	global_load_dword v206, v[184:185], off offset:512
	global_load_dword v207, v[184:185], off offset:640
	global_load_dword v208, v[184:185], off offset:768
	global_load_dword v209, v[184:185], off offset:896
	global_load_dword v210, v[184:185], off offset:1024
	global_load_dword v211, v[184:185], off offset:1152
	global_load_dword v212, v[184:185], off offset:1280
	global_load_dword v213, v[184:185], off offset:1408
	global_load_dword v214, v[184:185], off offset:1536
	global_load_dword v215, v[184:185], off offset:1664
	global_load_dword v216, v[184:185], off offset:1792
	global_load_dword v217, v[184:185], off offset:1920
	v_add_u32_e32 v218, 0x0, v44
	s_waitcnt vmcnt(14)
	v_mul_f32_e32 v186, v186, v202
	v_mul_f32_e32 v187, v187, v203
	ds_write2_b32 v218, v186, v187 offset1:32
	s_waitcnt vmcnt(12)
	v_mul_f32_e32 v188, v188, v204
	v_mul_f32_e32 v189, v189, v205
	ds_write2_b32 v218, v188, v189 offset0:64 offset1:96
	s_waitcnt vmcnt(10)
	v_mul_f32_e32 v190, v190, v206
	v_mul_f32_e32 v191, v191, v207
	ds_write2_b32 v218, v190, v191 offset0:128 offset1:160
	s_waitcnt vmcnt(8)
	v_mul_f32_e32 v192, v192, v208
	v_mul_f32_e32 v193, v193, v209
	ds_write2_b32 v218, v192, v193 offset0:192 offset1:224
	v_add_u32_e32 v218, 0x400, v44
	s_waitcnt vmcnt(6)
	v_mul_f32_e32 v194, v194, v210
	v_mul_f32_e32 v195, v195, v211
	ds_write2_b32 v218, v194, v195 offset1:32
	s_waitcnt vmcnt(4)
	v_mul_f32_e32 v196, v196, v212
	v_mul_f32_e32 v197, v197, v213
	ds_write2_b32 v218, v196, v197 offset0:64 offset1:96
	s_waitcnt vmcnt(2)
	v_mul_f32_e32 v198, v198, v214
	v_mul_f32_e32 v199, v199, v215
	ds_write2_b32 v218, v198, v199 offset0:128 offset1:160
	s_waitcnt vmcnt(0)
	v_mul_f32_e32 v200, v200, v216
	v_mul_f32_e32 v201, v201, v217
	ds_write2_b32 v218, v200, v201 offset0:192 offset1:224
	global_load_dword v186, v[182:183], off offset:2048
	global_load_dword v187, v[182:183], off offset:2176
	global_load_dword v188, v[182:183], off offset:2304
	global_load_dword v189, v[182:183], off offset:2432
	global_load_dword v190, v[182:183], off offset:2560
	global_load_dword v191, v[182:183], off offset:2688
	global_load_dword v192, v[182:183], off offset:2816
	global_load_dword v193, v[182:183], off offset:2944
	global_load_dword v194, v[182:183], off offset:3072
	global_load_dword v195, v[182:183], off offset:3200
	global_load_dword v196, v[182:183], off offset:3328
	global_load_dword v197, v[182:183], off offset:3456
	global_load_dword v198, v[182:183], off offset:3584
	global_load_dword v199, v[182:183], off offset:3712
	global_load_dword v200, v[182:183], off offset:3840
	global_load_dword v201, v[182:183], off offset:3968
	global_load_dword v202, v[184:185], off offset:2048
	global_load_dword v203, v[184:185], off offset:2176
	global_load_dword v204, v[184:185], off offset:2304
	global_load_dword v205, v[184:185], off offset:2432
	global_load_dword v206, v[184:185], off offset:2560
	global_load_dword v207, v[184:185], off offset:2688
	global_load_dword v208, v[184:185], off offset:2816
	global_load_dword v209, v[184:185], off offset:2944
	global_load_dword v210, v[184:185], off offset:3072
	global_load_dword v211, v[184:185], off offset:3200
	global_load_dword v212, v[184:185], off offset:3328
	global_load_dword v213, v[184:185], off offset:3456
	global_load_dword v214, v[184:185], off offset:3584
	global_load_dword v215, v[184:185], off offset:3712
	global_load_dword v216, v[184:185], off offset:3840
	global_load_dword v217, v[184:185], off offset:3968
	v_add_u32_e32 v218, 0x800, v44
	s_waitcnt vmcnt(14)
	v_mul_f32_e32 v186, v186, v202
	v_mul_f32_e32 v187, v187, v203
	ds_write2_b32 v218, v186, v187 offset1:32
	s_waitcnt vmcnt(12)
	v_mul_f32_e32 v188, v188, v204
	v_mul_f32_e32 v189, v189, v205
	ds_write2_b32 v218, v188, v189 offset0:64 offset1:96
	s_waitcnt vmcnt(10)
	v_mul_f32_e32 v190, v190, v206
	v_mul_f32_e32 v191, v191, v207
	ds_write2_b32 v218, v190, v191 offset0:128 offset1:160
	s_waitcnt vmcnt(8)
	v_mul_f32_e32 v192, v192, v208
	v_mul_f32_e32 v193, v193, v209
	ds_write2_b32 v218, v192, v193 offset0:192 offset1:224
	v_add_u32_e32 v218, 0xc00, v44
	s_waitcnt vmcnt(6)
	v_mul_f32_e32 v194, v194, v210
	v_mul_f32_e32 v195, v195, v211
	ds_write2_b32 v218, v194, v195 offset1:32
	s_waitcnt vmcnt(4)
	v_mul_f32_e32 v196, v196, v212
	v_mul_f32_e32 v197, v197, v213
	ds_write2_b32 v218, v196, v197 offset0:64 offset1:96
	s_waitcnt vmcnt(2)
	v_mul_f32_e32 v198, v198, v214
	v_mul_f32_e32 v199, v199, v215
	ds_write2_b32 v218, v198, v199 offset0:128 offset1:160
	s_waitcnt vmcnt(0)
	v_mul_f32_e32 v200, v200, v216
	v_mul_f32_e32 v201, v201, v217
	ds_write2_b32 v218, v200, v201 offset0:192 offset1:224
	v_ashrrev_i32_e32 v15, 31, v14
	v_lshlrev_b64 v[0:1], 12, v[14:15]
	v_lshl_add_u64 v[34:35], v[12:13], 0, v[0:1]
	s_mov_b32 s3, -4
	v_mov_b32_e32 v11, v46
	s_mov_b64 s[18:19], 0x8000
	s_waitcnt lgkmcnt(0)
	s_barrier
; template <int M> DEVI float shx(float v) { return __int_as_float(__builtin_amdgcn_ds_swizzle(__float_as_int(v), (M << 10) | 0x1f)); }
; DEVI float shx32(float v, int lane) { return __int_as_float(__builtin_amdgcn_ds_bpermute((lane ^ 32) << 2, __float_as_int(v))); }
; DEVI void sk_gemm(const float* __restrict__ A, int lda, int K, const float* __restrict__ W, int N, const float* __restrict__ gain,
;                   bool use_rs, float* __restrict__ out, int ldo, int mode, unsigned char* lds, int wv, int bid, int nblk) {
;     ...
;       const int ks = kc >> 5;
;       const int kb = (wave * 4 + kq) * ks;
;       const float* Wp = W + (size_t)(k0 + kb) * N + nl;
;       const float* Ap = As + kb;
; #pragma unroll 2
;       for (int k = 0; k < ks; k += 4) {
;         const float w0 = Wp[(size_t)(k + 0) * N], w1 = Wp[(size_t)(k + 1) * N], w2 = Wp[(size_t)(k + 2) * N], w3 = Wp[(size_t)(k + 3) * N];
; #pragma unroll
;         for (int b = 0; b < 16; ++b) { const float4 a = *(const float4*)(Ap + b * 1024 + k); acc[b] += a.x * w0 + a.y * w1 + a.z * w2 + a.w * w3; }
;       }
;     }
; #pragma unroll
;     for (int b = 0; b < 16; ++b) { float v = acc[b]; v += shx<16>(v); v += shx32(v, lane); if (kq == 0) red[(wave * 16 + b) * 16 + c16] = v; }
;     __syncthreads();
;     if (tid < 256) {
;       const int b = tid >> 4, c = tid & 15; float v = 0.f;
; #pragma unroll
;       for (int w = 0; w < 8; ++w) v += red[(w * 16 + b) * 16 + c];
;       const int nn = grp * 16 + c;
;       if (nn < N) {
;         if (use_rs) v *= rsS[b];
;         float* o = out + (size_t)b * ldo + nn;
;         if (mode == 1) *o += v; else if (mode == 2) { v = fmaxf(v, 0.f); *o = v * v; } else *o = v;
;       }
.LBB0_1011:
	s_mov_b64 s[18:19], 0x2000
	v_add_co_u32_e64 v20, s[4:5], s85, v34
	s_nop 0
	v_addc_co_u32_e64 v21, s[4:5], -1, v35, s[4:5]
	global_load_dword v186, v[20:21], off offset:-4096
	global_load_dword v187, v[20:21], off
	v_lshl_add_u64 v[20:21], v[20:21], 0, s[18:19]
	global_load_dword v188, v[20:21], off offset:-4096
	global_load_dword v189, v[20:21], off
	v_lshl_add_u64 v[20:21], v[20:21], 0, s[18:19]
	global_load_dword v190, v[20:21], off offset:-4096
	global_load_dword v191, v[20:21], off
	v_lshl_add_u64 v[20:21], v[20:21], 0, s[18:19]
	global_load_dword v192, v[20:21], off offset:-4096
	global_load_dword v193, v[20:21], off
	v_lshl_add_u64 v[20:21], v[20:21], 0, s[18:19]
	global_load_dword v194, v[20:21], off offset:-4096
	global_load_dword v195, v[20:21], off
	v_lshl_add_u64 v[20:21], v[20:21], 0, s[18:19]
	global_load_dword v196, v[20:21], off offset:-4096
	global_load_dword v197, v[20:21], off
	v_lshl_add_u64 v[20:21], v[20:21], 0, s[18:19]
	global_load_dword v198, v[20:21], off offset:-4096
	global_load_dword v199, v[20:21], off
	v_lshl_add_u64 v[20:21], v[20:21], 0, s[18:19]
	global_load_dword v200, v[20:21], off offset:-4096
	global_load_dword v201, v[20:21], off
	v_lshl_add_u64 v[20:21], v[20:21], 0, s[18:19]
	global_load_dword v202, v[20:21], off offset:-4096
	global_load_dword v203, v[20:21], off
	v_lshl_add_u64 v[20:21], v[20:21], 0, s[18:19]
	global_load_dword v204, v[20:21], off offset:-4096
	global_load_dword v205, v[20:21], off
	v_lshl_add_u64 v[20:21], v[20:21], 0, s[18:19]
	global_load_dword v206, v[20:21], off offset:-4096
	global_load_dword v207, v[20:21], off
	v_lshl_add_u64 v[20:21], v[20:21], 0, s[18:19]
	global_load_dword v208, v[20:21], off offset:-4096
	global_load_dword v209, v[20:21], off
	v_lshl_add_u64 v[20:21], v[20:21], 0, s[18:19]
	global_load_dword v210, v[20:21], off offset:-4096
	global_load_dword v211, v[20:21], off
	v_lshl_add_u64 v[20:21], v[20:21], 0, s[18:19]
	global_load_dword v212, v[20:21], off offset:-4096
	global_load_dword v213, v[20:21], off
	v_lshl_add_u64 v[20:21], v[20:21], 0, s[18:19]
	global_load_dword v214, v[20:21], off offset:-4096
	global_load_dword v215, v[20:21], off
	v_lshl_add_u64 v[20:21], v[20:21], 0, s[18:19]
	global_load_dword v216, v[20:21], off offset:-4096
	global_load_dword v217, v[20:21], off
	v_mbcnt_lo_u32_b32 v22, -1, 0
	v_mbcnt_hi_u32_b32 v22, -1, v22
	v_and_b32_e32 v22, 15, v22
	v_lshl_add_u32 v23, v22, 12, v46
	ds_read_b128 v[182:185], v23
	ds_read_b128 v[218:221], v23 offset:16
	s_waitcnt vmcnt(28) lgkmcnt(1)
	v_mfma_f32_16x16x4_f32 v[16:19], v182, v186, v[16:19]
	v_mfma_f32_16x16x4_f32 v[16:19], v183, v187, v[16:19]
	v_mfma_f32_16x16x4_f32 v[16:19], v184, v188, v[16:19]
	v_mfma_f32_16x16x4_f32 v[16:19], v185, v189, v[16:19]
	ds_read_b128 v[182:185], v23 offset:32
	s_waitcnt vmcnt(24) lgkmcnt(1)
	v_mfma_f32_16x16x4_f32 v[16:19], v218, v190, v[16:19]
	v_mfma_f32_16x16x4_f32 v[16:19], v219, v191, v[16:19]
	v_mfma_f32_16x16x4_f32 v[16:19], v220, v192, v[16:19]
	v_mfma_f32_16x16x4_f32 v[16:19], v221, v193, v[16:19]
	ds_read_b128 v[218:221], v23 offset:48
	s_waitcnt vmcnt(20) lgkmcnt(1)
	v_mfma_f32_16x16x4_f32 v[16:19], v182, v194, v[16:19]
	v_mfma_f32_16x16x4_f32 v[16:19], v183, v195, v[16:19]
	v_mfma_f32_16x16x4_f32 v[16:19], v184, v196, v[16:19]
	v_mfma_f32_16x16x4_f32 v[16:19], v185, v197, v[16:19]
	ds_read_b128 v[182:185], v23 offset:64
	s_waitcnt vmcnt(16) lgkmcnt(1)
	v_mfma_f32_16x16x4_f32 v[16:19], v218, v198, v[16:19]
	v_mfma_f32_16x16x4_f32 v[16:19], v219, v199, v[16:19]
	v_mfma_f32_16x16x4_f32 v[16:19], v220, v200, v[16:19]
	v_mfma_f32_16x16x4_f32 v[16:19], v221, v201, v[16:19]
	ds_read_b128 v[218:221], v23 offset:80
	s_waitcnt vmcnt(12) lgkmcnt(1)
	v_mfma_f32_16x16x4_f32 v[16:19], v182, v202, v[16:19]
	v_mfma_f32_16x16x4_f32 v[16:19], v183, v203, v[16:19]
	v_mfma_f32_16x16x4_f32 v[16:19], v184, v204, v[16:19]
	v_mfma_f32_16x16x4_f32 v[16:19], v185, v205, v[16:19]
	ds_read_b128 v[182:185], v23 offset:96
	s_waitcnt vmcnt(8) lgkmcnt(1)
	v_mfma_f32_16x16x4_f32 v[16:19], v218, v206, v[16:19]
	v_mfma_f32_16x16x4_f32 v[16:19], v219, v207, v[16:19]
	v_mfma_f32_16x16x4_f32 v[16:19], v220, v208, v[16:19]
	v_mfma_f32_16x16x4_f32 v[16:19], v221, v209, v[16:19]
	ds_read_b128 v[218:221], v23 offset:112
	s_waitcnt vmcnt(4) lgkmcnt(1)
	v_mfma_f32_16x16x4_f32 v[16:19], v182, v210, v[16:19]
	v_mfma_f32_16x16x4_f32 v[16:19], v183, v211, v[16:19]
	v_mfma_f32_16x16x4_f32 v[16:19], v184, v212, v[16:19]
	v_mfma_f32_16x16x4_f32 v[16:19], v185, v213, v[16:19]
	s_waitcnt vmcnt(0) lgkmcnt(0)
	v_mfma_f32_16x16x4_f32 v[16:19], v218, v214, v[16:19]
	v_mfma_f32_16x16x4_f32 v[16:19], v219, v215, v[16:19]
	v_mfma_f32_16x16x4_f32 v[16:19], v220, v216, v[16:19]
	v_mfma_f32_16x16x4_f32 v[16:19], v221, v217, v[16:19]
	s_add_i32 s3, s16, 0x400
	v_add_u32_e32 v14, 0x400, v14
	s_cmpk_gt_u32 s16, 0xbff
	s_mov_b32 s16, s3
	s_cbranch_scc0 .LBB0_1008
	s_nop 7
	s_nop 3
	v_mbcnt_lo_u32_b32 v22, -1, 0
	v_mbcnt_hi_u32_b32 v22, -1, v22
	v_lshrrev_b32_e32 v22, 4, v22
	v_lshl_add_u32 v22, v22, 8, v47
	ds_write_b32 v22, v16
	ds_write_b32 v22, v17 offset:64
	ds_write_b32 v22, v18 offset:128
	ds_write_b32 v22, v19 offset:192
	v_lshl_or_b32 v0, s2, 4, v41
	s_movk_i32 s3, 0x400
	v_cmp_gt_i32_e64 s[4:5], s3, v0
	s_and_b64 s[16:17], s[0:1], s[4:5]
	s_waitcnt lgkmcnt(0)
	s_barrier
	s_and_saveexec_b64 s[4:5], s[16:17]
	s_cbranch_execz .LBB0_1006
	ds_read2st64_b32 v[2:3], v43 offset1:4
	v_ashrrev_i32_e32 v1, 31, v0
	v_lshl_add_u64 v[0:1], v[0:1], 2, v[8:9]
	s_waitcnt lgkmcnt(0)
	v_add_f32_e32 v2, 0, v2
	v_add_f32_e32 v11, v2, v3
	ds_read2st64_b32 v[2:3], v43 offset0:8 offset1:12
	s_waitcnt lgkmcnt(0)
	v_add_f32_e32 v2, v11, v2
	v_add_f32_e32 v11, v2, v3
	ds_read2st64_b32 v[2:3], v43 offset0:16 offset1:20
	s_waitcnt lgkmcnt(0)
	v_add_f32_e32 v2, v11, v2
	v_add_f32_e32 v11, v2, v3
	ds_read2st64_b32 v[2:3], v43 offset0:24 offset1:28
	s_waitcnt lgkmcnt(0)
	v_add_f32_e32 v2, v11, v2
	v_add_f32_e32 v2, v2, v3
	global_load_dword v3, v[0:1], off
	s_waitcnt vmcnt(0)
	v_add_f32_e32 v2, v2, v3
	global_store_dword v[0:1], v2, off
	s_branch .LBB0_1006

; template <int M> DEVI float shx(float v) { return __int_as_float(__builtin_amdgcn_ds_swizzle(__float_as_int(v), (M << 10) | 0x1f)); }
; DEVI void sk_gemm(const float* __restrict__ A, int lda, int K, const float* __restrict__ W, int N, const float* __restrict__ gain,
;                   bool use_rs, float* __restrict__ out, int ldo, int mode, unsigned char* lds, int wv, int bid, int nblk) {
;     ...
;       __syncthreads();
;       {
;         const int b = tid >> 5, j = tid & 31; float ss = 0.f;
; #pragma unroll 8
;         for (int k = j; k < kc; k += 32) { const float v = A[(size_t)b * lda + k0 + k]; ss += v * v; As[b * 1024 + k] = v * gain[k0 + k]; }
;         if (use_rs) { ss += shx<16>(ss); ss += shx<8>(ss); ss += shx<4>(ss); ss += shx<2>(ss); ss += shx<1>(ss); if (j == 0) rsS[b] = rsqrtf(ss / (float)K + 1e-6f); }
;       }
;       __syncthreads();
.LBB0_1766:
	v_mov_b32_e32 v32, v2
	v_lshl_add_u64 v[182:183], v[32:33], 2, v[0:1]
	v_add_u32_e32 v32, s18, v2
	v_lshl_add_u64 v[184:185], v[32:33], 2, s[90:91]
	global_load_dword v186, v[182:183], off offset:0
	global_load_dword v187, v[182:183], off offset:128
	global_load_dword v188, v[182:183], off offset:256
	global_load_dword v189, v[182:183], off offset:384
	global_load_dword v190, v[182:183], off offset:512
	global_load_dword v191, v[182:183], off offset:640
	global_load_dword v192, v[182:183], off offset:768
	global_load_dword v193, v[182:183], off offset:896
	global_load_dword v194, v[182:183], off offset:1024
	global_load_dword v195, v[182:183], off offset:1152
	global_load_dword v196, v[182:183], off offset:1280
	global_load_dword v197, v[182:183], off offset:1408
	global_load_dword v198, v[182:183], off offset:1536
	global_load_dword v199, v[182:183], off offset:1664
	global_load_dword v200, v[182:183], off offset:1792
	global_load_dword v201, v[182:183], off offset:1920
	global_load_dword v202, v[184:185], off offset:0
	global_load_dword v203, v[184:185], off offset:128
	global_load_dword v204, v[184:185], off offset:256
	global_load_dword v205, v[184:185], off offset:384
	global_load_dword v206, v[184:185], off offset:512
	global_load_dword v207, v[184:185], off offset:640
	global_load_dword v208, v[184:185], off offset:768
	global_load_dword v209, v[184:185], off offset:896
	global_load_dword v210, v[184:185], off offset:1024
	global_load_dword v211, v[184:185], off offset:1152
	global_load_dword v212, v[184:185], off offset:1280
	global_load_dword v213, v[184:185], off offset:1408
	global_load_dword v214, v[184:185], off offset:1536
	global_load_dword v215, v[184:185], off offset:1664
	global_load_dword v216, v[184:185], off offset:1792
	global_load_dword v217, v[184:185], off offset:1920
	v_add_u32_e32 v218, 0x0, v44
	s_waitcnt vmcnt(14)
	v_mul_f32_e32 v186, v186, v202
	v_mul_f32_e32 v187, v187, v203
	ds_write2_b32 v218, v186, v187 offset1:32
	s_waitcnt vmcnt(12)
	v_mul_f32_e32 v188, v188, v204
	v_mul_f32_e32 v189, v189, v205
	ds_write2_b32 v218, v188, v189 offset0:64 offset1:96
	s_waitcnt vmcnt(10)
	v_mul_f32_e32 v190, v190, v206
	v_mul_f32_e32 v191, v191, v207
	ds_write2_b32 v218, v190, v191 offset0:128 offset1:160
	s_waitcnt vmcnt(8)
	v_mul_f32_e32 v192, v192, v208
	v_mul_f32_e32 v193, v193, v209
	ds_write2_b32 v218, v192, v193 offset0:192 offset1:224
	v_add_u32_e32 v218, 0x400, v44
	s_waitcnt vmcnt(6)
	v_mul_f32_e32 v194, v194, v210
	v_mul_f32_e32 v195, v195, v211
	ds_write2_b32 v218, v194, v195 offset1:32
	s_waitcnt vmcnt(4)
	v_mul_f32_e32 v196, v196, v212
	v_mul_f32_e32 v197, v197, v213
	ds_write2_b32 v218, v196, v197 offset0:64 offset1:96
	s_waitcnt vmcnt(2)
	v_mul_f32_e32 v198, v198, v214
	v_mul_f32_e32 v199, v199, v215
	ds_write2_b32 v218, v198, v199 offset0:128 offset1:160
	s_waitcnt vmcnt(0)
	v_mul_f32_e32 v200, v200, v216
	v_mul_f32_e32 v201, v201, v217
	ds_write2_b32 v218, v200, v201 offset0:192 offset1:224
	global_load_dword v186, v[182:183], off offset:2048
	global_load_dword v187, v[182:183], off offset:2176
	global_load_dword v188, v[182:183], off offset:2304
	global_load_dword v189, v[182:183], off offset:2432
	global_load_dword v190, v[182:183], off offset:2560
	global_load_dword v191, v[182:183], off offset:2688
	global_load_dword v192, v[182:183], off offset:2816
	global_load_dword v193, v[182:183], off offset:2944
	global_load_dword v194, v[182:183], off offset:3072
	global_load_dword v195, v[182:183], off offset:3200
	global_load_dword v196, v[182:183], off offset:3328
	global_load_dword v197, v[182:183], off offset:3456
	global_load_dword v198, v[182:183], off offset:3584
	global_load_dword v199, v[182:183], off offset:3712
	global_load_dword v200, v[182:183], off offset:3840
	global_load_dword v201, v[182:183], off offset:3968
	global_load_dword v202, v[184:185], off offset:2048
	global_load_dword v203, v[184:185], off offset:2176
	global_load_dword v204, v[184:185], off offset:2304
	global_load_dword v205, v[184:185], off offset:2432
	global_load_dword v206, v[184:185], off offset:2560
	global_load_dword v207, v[184:185], off offset:2688
	global_load_dword v208, v[184:185], off offset:2816
	global_load_dword v209, v[184:185], off offset:2944
	global_load_dword v210, v[184:185], off offset:3072
	global_load_dword v211, v[184:185], off offset:3200
	global_load_dword v212, v[184:185], off offset:3328
	global_load_dword v213, v[184:185], off offset:3456
	global_load_dword v214, v[184:185], off offset:3584
	global_load_dword v215, v[184:185], off offset:3712
	global_load_dword v216, v[184:185], off offset:3840
	global_load_dword v217, v[184:185], off offset:3968
	v_add_u32_e32 v218, 0x800, v44
	s_waitcnt vmcnt(14)
	v_mul_f32_e32 v186, v186, v202
	v_mul_f32_e32 v187, v187, v203
	ds_write2_b32 v218, v186, v187 offset1:32
	s_waitcnt vmcnt(12)
	v_mul_f32_e32 v188, v188, v204
	v_mul_f32_e32 v189, v189, v205
	ds_write2_b32 v218, v188, v189 offset0:64 offset1:96
	s_waitcnt vmcnt(10)
	v_mul_f32_e32 v190, v190, v206
	v_mul_f32_e32 v191, v191, v207
	ds_write2_b32 v218, v190, v191 offset0:128 offset1:160
	s_waitcnt vmcnt(8)
	v_mul_f32_e32 v192, v192, v208
	v_mul_f32_e32 v193, v193, v209
	ds_write2_b32 v218, v192, v193 offset0:192 offset1:224
	v_add_u32_e32 v218, 0xc00, v44
	s_waitcnt vmcnt(6)
	v_mul_f32_e32 v194, v194, v210
	v_mul_f32_e32 v195, v195, v211
	ds_write2_b32 v218, v194, v195 offset1:32
	s_waitcnt vmcnt(4)
	v_mul_f32_e32 v196, v196, v212
	v_mul_f32_e32 v197, v197, v213
	ds_write2_b32 v218, v196, v197 offset0:64 offset1:96
	s_waitcnt vmcnt(2)
	v_mul_f32_e32 v198, v198, v214
	v_mul_f32_e32 v199, v199, v215
	ds_write2_b32 v218, v198, v199 offset0:128 offset1:160
	s_waitcnt vmcnt(0)
	v_mul_f32_e32 v200, v200, v216
	v_mul_f32_e32 v201, v201, v217
	ds_write2_b32 v218, v200, v201 offset0:192 offset1:224
	v_ashrrev_i32_e32 v15, 31, v14
	v_lshlrev_b64 v[0:1], 12, v[14:15]
	v_lshl_add_u64 v[34:35], v[12:13], 0, v[0:1]
	s_mov_b32 s3, -4
	v_mov_b32_e32 v11, v46
	s_mov_b64 s[20:21], 0x8000
	s_waitcnt lgkmcnt(0)
	s_barrier
; template <int M> DEVI float shx(float v) { return __int_as_float(__builtin_amdgcn_ds_swizzle(__float_as_int(v), (M << 10) | 0x1f)); }
; DEVI float shx32(float v, int lane) { return __int_as_float(__builtin_amdgcn_ds_bpermute((lane ^ 32) << 2, __float_as_int(v))); }
; DEVI void sk_gemm(const float* __restrict__ A, int lda, int K, const float* __restrict__ W, int N, const float* __restrict__ gain,
;                   bool use_rs, float* __restrict__ out, int ldo, int mode, unsigned char* lds, int wv, int bid, int nblk) {
;     ...
;       const int ks = kc >> 5;
;       const int kb = (wave * 4 + kq) * ks;
;       const float* Wp = W + (size_t)(k0 + kb) * N + nl;
;       const float* Ap = As + kb;
; #pragma unroll 2
;       for (int k = 0; k < ks; k += 4) {
;         const float w0 = Wp[(size_t)(k + 0) * N], w1 = Wp[(size_t)(k + 1) * N], w2 = Wp[(size_t)(k + 2) * N], w3 = Wp[(size_t)(k + 3) * N];
; #pragma unroll
;         for (int b = 0; b < 16; ++b) { const float4 a = *(const float4*)(Ap + b * 1024 + k); acc[b] += a.x * w0 + a.y * w1 + a.z * w2 + a.w * w3; }
;       }
;     }
; #pragma unroll
;     for (int b = 0; b < 16; ++b) { float v = acc[b]; v += shx<16>(v); v += shx32(v, lane); if (kq == 0) red[(wave * 16 + b) * 16 + c16] = v; }
;     __syncthreads();
;     if (tid < 256) {
;       const int b = tid >> 4, c = tid & 15; float v = 0.f;
; #pragma unroll
;       for (int w = 0; w < 8; ++w) v += red[(w * 16 + b) * 16 + c];
;       const int nn = grp * 16 + c;
;       if (nn < N) {
;         if (use_rs) v *= rsS[b];
;         float* o = out + (size_t)b * ldo + nn;
;         if (mode == 1) *o += v; else if (mode == 2) { v = fmaxf(v, 0.f); *o = v * v; } else *o = v;
;       }
.LBB0_1768:
	s_mov_b64 s[20:21], 0x2000
	v_add_co_u32_e64 v20, s[6:7], s85, v34
	s_nop 0
	v_addc_co_u32_e64 v21, s[6:7], -1, v35, s[6:7]
	global_load_dword v186, v[20:21], off offset:-4096
	global_load_dword v187, v[20:21], off
	v_lshl_add_u64 v[20:21], v[20:21], 0, s[20:21]
	global_load_dword v188, v[20:21], off offset:-4096
	global_load_dword v189, v[20:21], off
	v_lshl_add_u64 v[20:21], v[20:21], 0, s[20:21]
	global_load_dword v190, v[20:21], off offset:-4096
	global_load_dword v191, v[20:21], off
	v_lshl_add_u64 v[20:21], v[20:21], 0, s[20:21]
	global_load_dword v192, v[20:21], off offset:-4096
	global_load_dword v193, v[20:21], off
	v_lshl_add_u64 v[20:21], v[20:21], 0, s[20:21]
	global_load_dword v194, v[20:21], off offset:-4096
	global_load_dword v195, v[20:21], off
	v_lshl_add_u64 v[20:21], v[20:21], 0, s[20:21]
	global_load_dword v196, v[20:21], off offset:-4096
	global_load_dword v197, v[20:21], off
	v_lshl_add_u64 v[20:21], v[20:21], 0, s[20:21]
	global_load_dword v198, v[20:21], off offset:-4096
	global_load_dword v199, v[20:21], off
	v_lshl_add_u64 v[20:21], v[20:21], 0, s[20:21]
	global_load_dword v200, v[20:21], off offset:-4096
	global_load_dword v201, v[20:21], off
	v_lshl_add_u64 v[20:21], v[20:21], 0, s[20:21]
	global_load_dword v202, v[20:21], off offset:-4096
	global_load_dword v203, v[20:21], off
	v_lshl_add_u64 v[20:21], v[20:21], 0, s[20:21]
	global_load_dword v204, v[20:21], off offset:-4096
	global_load_dword v205, v[20:21], off
	v_lshl_add_u64 v[20:21], v[20:21], 0, s[20:21]
	global_load_dword v206, v[20:21], off offset:-4096
	global_load_dword v207, v[20:21], off
	v_lshl_add_u64 v[20:21], v[20:21], 0, s[20:21]
	global_load_dword v208, v[20:21], off offset:-4096
	global_load_dword v209, v[20:21], off
	v_lshl_add_u64 v[20:21], v[20:21], 0, s[20:21]
	global_load_dword v210, v[20:21], off offset:-4096
	global_load_dword v211, v[20:21], off
	v_lshl_add_u64 v[20:21], v[20:21], 0, s[20:21]
	global_load_dword v212, v[20:21], off offset:-4096
	global_load_dword v213, v[20:21], off
	v_lshl_add_u64 v[20:21], v[20:21], 0, s[20:21]
	global_load_dword v214, v[20:21], off offset:-4096
	global_load_dword v215, v[20:21], off
	v_lshl_add_u64 v[20:21], v[20:21], 0, s[20:21]
	global_load_dword v216, v[20:21], off offset:-4096
	global_load_dword v217, v[20:21], off
	v_mbcnt_lo_u32_b32 v22, -1, 0
	v_mbcnt_hi_u32_b32 v22, -1, v22
	v_and_b32_e32 v22, 15, v22
	v_lshl_add_u32 v23, v22, 12, v46
	ds_read_b128 v[182:185], v23
	ds_read_b128 v[218:221], v23 offset:16
	s_waitcnt vmcnt(28) lgkmcnt(1)
	v_mfma_f32_16x16x4_f32 v[16:19], v182, v186, v[16:19]
	v_mfma_f32_16x16x4_f32 v[16:19], v183, v187, v[16:19]
	v_mfma_f32_16x16x4_f32 v[16:19], v184, v188, v[16:19]
	v_mfma_f32_16x16x4_f32 v[16:19], v185, v189, v[16:19]
	ds_read_b128 v[182:185], v23 offset:32
	s_waitcnt vmcnt(24) lgkmcnt(1)
	v_mfma_f32_16x16x4_f32 v[16:19], v218, v190, v[16:19]
	v_mfma_f32_16x16x4_f32 v[16:19], v219, v191, v[16:19]
	v_mfma_f32_16x16x4_f32 v[16:19], v220, v192, v[16:19]
	v_mfma_f32_16x16x4_f32 v[16:19], v221, v193, v[16:19]
	ds_read_b128 v[218:221], v23 offset:48
	s_waitcnt vmcnt(20) lgkmcnt(1)
	v_mfma_f32_16x16x4_f32 v[16:19], v182, v194, v[16:19]
	v_mfma_f32_16x16x4_f32 v[16:19], v183, v195, v[16:19]
	v_mfma_f32_16x16x4_f32 v[16:19], v184, v196, v[16:19]
	v_mfma_f32_16x16x4_f32 v[16:19], v185, v197, v[16:19]
	ds_read_b128 v[182:185], v23 offset:64
	s_waitcnt vmcnt(16) lgkmcnt(1)
	v_mfma_f32_16x16x4_f32 v[16:19], v218, v198, v[16:19]
	v_mfma_f32_16x16x4_f32 v[16:19], v219, v199, v[16:19]
	v_mfma_f32_16x16x4_f32 v[16:19], v220, v200, v[16:19]
	v_mfma_f32_16x16x4_f32 v[16:19], v221, v201, v[16:19]
	ds_read_b128 v[218:221], v23 offset:80
	s_waitcnt vmcnt(12) lgkmcnt(1)
	v_mfma_f32_16x16x4_f32 v[16:19], v182, v202, v[16:19]
	v_mfma_f32_16x16x4_f32 v[16:19], v183, v203, v[16:19]
	v_mfma_f32_16x16x4_f32 v[16:19], v184, v204, v[16:19]
	v_mfma_f32_16x16x4_f32 v[16:19], v185, v205, v[16:19]
	ds_read_b128 v[182:185], v23 offset:96
	s_waitcnt vmcnt(8) lgkmcnt(1)
	v_mfma_f32_16x16x4_f32 v[16:19], v218, v206, v[16:19]
	v_mfma_f32_16x16x4_f32 v[16:19], v219, v207, v[16:19]
	v_mfma_f32_16x16x4_f32 v[16:19], v220, v208, v[16:19]
	v_mfma_f32_16x16x4_f32 v[16:19], v221, v209, v[16:19]
	ds_read_b128 v[218:221], v23 offset:112
	s_waitcnt vmcnt(4) lgkmcnt(1)
	v_mfma_f32_16x16x4_f32 v[16:19], v182, v210, v[16:19]
	v_mfma_f32_16x16x4_f32 v[16:19], v183, v211, v[16:19]
	v_mfma_f32_16x16x4_f32 v[16:19], v184, v212, v[16:19]
	v_mfma_f32_16x16x4_f32 v[16:19], v185, v213, v[16:19]
	s_waitcnt vmcnt(0) lgkmcnt(0)
	v_mfma_f32_16x16x4_f32 v[16:19], v218, v214, v[16:19]
	v_mfma_f32_16x16x4_f32 v[16:19], v219, v215, v[16:19]
	v_mfma_f32_16x16x4_f32 v[16:19], v220, v216, v[16:19]
	v_mfma_f32_16x16x4_f32 v[16:19], v221, v217, v[16:19]
	s_add_i32 s3, s18, 0x400
	v_add_u32_e32 v14, 0x400, v14
	s_cmpk_gt_u32 s18, 0xbff
	s_mov_b32 s18, s3
	s_cbranch_scc0 .LBB0_1765
	s_nop 7
	s_nop 3
	v_mbcnt_lo_u32_b32 v22, -1, 0
	v_mbcnt_hi_u32_b32 v22, -1, v22
	v_lshrrev_b32_e32 v22, 4, v22
	v_lshl_add_u32 v22, v22, 8, v47
	ds_write_b32 v22, v16
	ds_write_b32 v22, v17 offset:64
	ds_write_b32 v22, v18 offset:128
	ds_write_b32 v22, v19 offset:192
	v_lshl_or_b32 v0, s2, 4, v41
	s_movk_i32 s3, 0x400
	v_cmp_gt_i32_e64 s[6:7], s3, v0
	s_and_b64 s[18:19], s[4:5], s[6:7]
	s_waitcnt lgkmcnt(0)
	s_barrier
	s_and_saveexec_b64 s[6:7], s[18:19]
	s_cbranch_execz .LBB0_1763
	ds_read2st64_b32 v[2:3], v43 offset1:4
	v_ashrrev_i32_e32 v1, 31, v0
	v_lshl_add_u64 v[0:1], v[0:1], 2, v[8:9]
	s_waitcnt lgkmcnt(0)
	v_add_f32_e32 v2, 0, v2
	v_add_f32_e32 v11, v2, v3
	ds_read2st64_b32 v[2:3], v43 offset0:8 offset1:12
	s_waitcnt lgkmcnt(0)
	v_add_f32_e32 v2, v11, v2
	v_add_f32_e32 v11, v2, v3
	ds_read2st64_b32 v[2:3], v43 offset0:16 offset1:20
	s_waitcnt lgkmcnt(0)
	v_add_f32_e32 v2, v11, v2
	v_add_f32_e32 v11, v2, v3
	ds_read2st64_b32 v[2:3], v43 offset0:24 offset1:28
	s_waitcnt lgkmcnt(0)
	v_add_f32_e32 v2, v11, v2
	v_add_f32_e32 v2, v2, v3
	global_load_dword v3, v[0:1], off
	s_waitcnt vmcnt(0)
	v_add_f32_e32 v2, v2, v3
	global_store_dword v[0:1], v2, off
	s_branch .LBB0_1763
